# attention NOMAX loops: row-sum adds moved from the pre-barrier tail into the QK/PV MFMA shadow (MFMA-VALU interleave)
# baseline (speedup 1.0000x reference)
.LBB0_547:
	ds_read_b128 v[32:35], v105 offset:21504
	ds_read_b128 v[146:149], v105 offset:21536
	ds_read_b128 v[48:51], v105 offset:28160
	ds_read_b128 v[166:169], v105 offset:28192
	ds_read_b128 v[170:173], v105 offset:21568
	ds_read_b128 v[174:177], v105 offset:21600
	ds_read_b128 v[178:181], v105 offset:28224
	ds_read_b128 v[182:185], v105 offset:28256
	ds_read_b128 v[186:189], v105 offset:21632
	ds_read_b128 v[190:193], v105 offset:21664
	ds_read_b128 v[194:197], v105 offset:28288
	ds_read_b128 v[198:201], v105 offset:28320
	s_waitcnt lgkmcnt(11)
	v_mfma_f32_32x32x16_bf16 v[32:47], v[32:35], v[64:67], 0
	v_add_f32_e32 v226, v121, v125
	v_add_f32_e32 v227, v135, v136
	v_add_f32_e32 v226, v126, v226
	s_waitcnt lgkmcnt(9)
	v_mfma_f32_32x32x16_bf16 v[48:63], v[48:51], v[64:67], 0
	v_add_f32_e32 v227, v137, v227
	v_add_f32_e32 v226, v127, v226
	v_add_f32_e32 v227, v138, v227
	v_mfma_f32_32x32x16_bf16 v[32:47], v[146:149], v[68:71], v[32:47]
	v_add_f32_e32 v226, v131, v226
	v_add_f32_e32 v227, v139, v227
	v_add_f32_e32 v226, v132, v226
	s_waitcnt lgkmcnt(8)
	v_mfma_f32_32x32x16_bf16 v[48:63], v[166:169], v[68:71], v[48:63]
	v_add_f32_e32 v227, v140, v227
	v_add_f32_e32 v226, v133, v226
	v_add_f32_e32 v227, v141, v227
	s_waitcnt lgkmcnt(7)
	v_mfma_f32_32x32x16_bf16 v[32:47], v[170:173], v[72:75], v[32:47]
	v_add_f32_e32 v226, v134, v226
	v_add_f32_e32 v227, v142, v227
	v_add_f32_e32 v226, v143, v226
	s_waitcnt lgkmcnt(5)
	v_mfma_f32_32x32x16_bf16 v[48:63], v[178:181], v[72:75], v[48:63]
	v_add_f32_e32 v227, v158, v227
	v_add_f32_e32 v226, v144, v226
	v_add_f32_e32 v227, v159, v227
	v_mfma_f32_32x32x16_bf16 v[32:47], v[174:177], v[76:79], v[32:47]
	v_add_f32_e32 v226, v152, v226
	v_add_f32_e32 v227, v160, v227
	v_add_f32_e32 v226, v153, v226
	s_waitcnt lgkmcnt(4)
	v_mfma_f32_32x32x16_bf16 v[48:63], v[182:185], v[76:79], v[48:63]
	v_add_f32_e32 v227, v161, v227
	v_add_f32_e32 v226, v154, v226
	v_add_f32_e32 v227, v162, v227
	s_waitcnt lgkmcnt(3)
	v_mfma_f32_32x32x16_bf16 v[32:47], v[186:189], v[80:83], v[32:47]
	v_add_f32_e32 v226, v155, v226
	v_add_f32_e32 v227, v163, v227
	v_add_f32_e32 v226, v156, v226
	s_waitcnt lgkmcnt(1)
	v_mfma_f32_32x32x16_bf16 v[48:63], v[194:197], v[80:83], v[48:63]
	v_add_f32_e32 v227, v164, v227
	v_add_f32_e32 v226, v157, v226
	v_add_f32_e32 v227, v165, v227
	v_mfma_f32_32x32x16_bf16 v[32:47], v[190:193], v[84:87], v[32:47]
	v_add_f32_e32 v226, v226, v227
	s_waitcnt lgkmcnt(0)
	v_mfma_f32_32x32x16_bf16 v[48:63], v[198:201], v[84:87], v[48:63]
	s_nop 9
	v_exp_f32_e32 v32, v32
	v_exp_f32_e32 v33, v33
	v_exp_f32_e32 v34, v34
	v_exp_f32_e32 v35, v35
	v_exp_f32_e32 v36, v36
	v_exp_f32_e32 v37, v37
	v_exp_f32_e32 v38, v38
	v_exp_f32_e32 v48, v48
	v_exp_f32_e32 v49, v49
	v_exp_f32_e32 v50, v50
	v_exp_f32_e32 v51, v51
	v_exp_f32_e32 v52, v52
	v_exp_f32_e32 v53, v53
	v_exp_f32_e32 v54, v54
	v_exp_f32_e32 v39, v39
	v_exp_f32_e32 v55, v55
	v_exp_f32_e32 v40, v40
	v_exp_f32_e32 v56, v56
	v_exp_f32_e32 v41, v41
	v_exp_f32_e32 v57, v57
	v_exp_f32_e32 v42, v42
	v_exp_f32_e32 v58, v58
	v_exp_f32_e32 v43, v43
	v_exp_f32_e32 v59, v59
	v_exp_f32_e32 v44, v44
	v_exp_f32_e32 v60, v60
	v_exp_f32_e32 v45, v45
	v_exp_f32_e32 v61, v61
	v_exp_f32_e32 v46, v46
	v_exp_f32_e32 v62, v62
	v_exp_f32_e32 v47, v47
	v_exp_f32_e32 v63, v63
	ds_read_b64_tr_b16 v[146:147], v218 offset:34816
	ds_read_b64_tr_b16 v[148:149], v218 offset:35840
	ds_read_b64_tr_b16 v[168:169], v218 offset:36096
	ds_read_b64_tr_b16 v[166:167], v218 offset:35072
	ds_read_b64_tr_b16 v[170:171], v218 offset:36864
	ds_read_b64_tr_b16 v[172:173], v218 offset:37888
	ds_read_b64_tr_b16 v[176:177], v218 offset:38144
	ds_read_b64_tr_b16 v[174:175], v218 offset:37120
	ds_read_b64_tr_b16 v[178:179], v218 offset:38912
	ds_read_b64_tr_b16 v[180:181], v218 offset:39936
	ds_read_b64_tr_b16 v[184:185], v218 offset:40192
	ds_read_b64_tr_b16 v[182:183], v218 offset:39168
	ds_read_b64_tr_b16 v[186:187], v218 offset:40960
	ds_read_b64_tr_b16 v[188:189], v218 offset:41984
	ds_read_b64_tr_b16 v[192:193], v218 offset:42240
	ds_read_b64_tr_b16 v[190:191], v218 offset:41216
	v_cvt_pk_bf16_f32 v194, v32, v33
	v_cvt_pk_bf16_f32 v195, v34, v35
	v_cvt_pk_bf16_f32 v196, v36, v37
	v_cvt_pk_bf16_f32 v197, v38, v39
	s_andn2_b64 vcc, exec, s[8:9]
	s_waitcnt lgkmcnt(14)
	v_mfma_f32_32x32x16_bf16 v[16:31], v[146:149], v[194:197], v[16:31]
	v_add_f32_e32 v228, v32, v33
	v_add_f32_e32 v229, v48, v49
	v_add_f32_e32 v228, v34, v228
	v_add_f32_e32 v229, v50, v229
	v_cvt_pk_bf16_f32 v146, v48, v49
	v_cvt_pk_bf16_f32 v147, v50, v51
	v_cvt_pk_bf16_f32 v148, v52, v53
	v_cvt_pk_bf16_f32 v149, v54, v55
	s_waitcnt lgkmcnt(12)
	v_mfma_f32_32x32x16_bf16 v[0:15], v[166:169], v[194:197], v[0:15]
	v_add_f32_e32 v228, v35, v228
	v_add_f32_e32 v229, v51, v229
	v_add_f32_e32 v228, v36, v228
	v_add_f32_e32 v229, v52, v229
	v_cvt_pk_bf16_f32 v166, v40, v41
	v_cvt_pk_bf16_f32 v167, v42, v43
	v_cvt_pk_bf16_f32 v168, v44, v45
	v_cvt_pk_bf16_f32 v169, v46, v47
	s_waitcnt lgkmcnt(10)
	v_mfma_f32_32x32x16_bf16 v[16:31], v[170:173], v[166:169], v[16:31]
	v_add_f32_e32 v228, v37, v228
	v_add_f32_e32 v229, v53, v229
	v_add_f32_e32 v228, v38, v228
	v_add_f32_e32 v229, v54, v229
	s_waitcnt lgkmcnt(8)
	v_mfma_f32_32x32x16_bf16 v[0:15], v[174:177], v[166:169], v[0:15]
	v_add_f32_e32 v228, v39, v228
	v_add_f32_e32 v229, v55, v229
	v_add_f32_e32 v228, v40, v228
	v_add_f32_e32 v229, v56, v229
	s_waitcnt lgkmcnt(6)
	v_mfma_f32_32x32x16_bf16 v[16:31], v[178:181], v[146:149], v[16:31]
	v_add_f32_e32 v228, v41, v228
	v_add_f32_e32 v229, v57, v229
	v_add_f32_e32 v228, v42, v228
	v_add_f32_e32 v229, v58, v229
	s_waitcnt lgkmcnt(4)
	v_mfma_f32_32x32x16_bf16 v[0:15], v[182:185], v[146:149], v[0:15]
	v_add_f32_e32 v228, v43, v228
	v_add_f32_e32 v229, v59, v229
	v_add_f32_e32 v228, v44, v228
	v_add_f32_e32 v229, v60, v229
	v_cvt_pk_bf16_f32 v146, v56, v57
	v_cvt_pk_bf16_f32 v147, v58, v59
	v_cvt_pk_bf16_f32 v148, v60, v61
	v_cvt_pk_bf16_f32 v149, v62, v63
	s_waitcnt lgkmcnt(2)
	v_mfma_f32_32x32x16_bf16 v[16:31], v[186:189], v[146:149], v[16:31]
	v_add_f32_e32 v228, v45, v228
	v_add_f32_e32 v229, v61, v229
	v_add_f32_e32 v228, v46, v228
	v_add_f32_e32 v229, v62, v229
	s_waitcnt lgkmcnt(0)
	v_mfma_f32_32x32x16_bf16 v[0:15], v[190:193], v[146:149], v[0:15]
	v_add_f32_e32 v228, v47, v228
	v_add_f32_e32 v229, v63, v229
	v_add_f32_e32 v228, v228, v229
	s_cbranch_vccnz .LBB0_549
	s_add_i32 s13, s10, 2
	s_cmp_ge_u32 s11, s13
	s_cbranch_scc1 .Lmla_w1_tail
	s_waitcnt vmcnt(5)
	ds_write_b128 v220, v[88:91]
	s_waitcnt vmcnt(4)
	ds_write_b128 v219, v[92:95] offset:13312
	s_waitcnt vmcnt(3)
	ds_write_b64 v129, v[116:117] offset:128
	s_branch .LBB0_549

.LBB0_549:
	v_add_f32_e32 v226, v226, v228
	v_add_f32_e32 v124, v124, v226
	s_andn2_b64 vcc, exec, s[4:5]
	v_add_u32_e32 v120, 0x80, v120
	s_waitcnt lgkmcnt(0)
	s_barrier
	s_cbranch_vccz .LBB0_518
	s_mov_b32 s12, s11
	s_branch .LBB0_541

.LBB0_584:
	ds_read_b128 v[32:35], v194 offset:17408
	ds_read_b128 v[140:143], v194 offset:17440
	ds_read_b128 v[36:39], v194 offset:22016
	ds_read_b128 v[146:149], v194 offset:22048
	ds_read_b128 v[152:155], v194 offset:17472
	ds_read_b128 v[156:159], v194 offset:17504
	ds_read_b128 v[160:163], v194 offset:22080
	ds_read_b128 v[164:167], v194 offset:22112
	ds_read_b64_tr_b16 v[168:169], v218 offset:26624
	ds_read_b64_tr_b16 v[170:171], v218 offset:27648
	ds_read_b64_tr_b16 v[174:175], v218 offset:27904
	ds_read_b64_tr_b16 v[172:173], v218 offset:26880
	ds_read_b64_tr_b16 v[176:177], v218 offset:28672
	ds_read_b64_tr_b16 v[178:179], v218 offset:29696
	ds_read_b64_tr_b16 v[182:183], v218 offset:29952
	ds_read_b64_tr_b16 v[180:181], v218 offset:28928
	ds_read_b64_tr_b16 v[184:185], v218 offset:30720
	ds_read_b64_tr_b16 v[186:187], v218 offset:31744
	ds_read_b64_tr_b16 v[190:191], v218 offset:32000
	ds_read_b64_tr_b16 v[188:189], v218 offset:30976
	ds_read_b64_tr_b16 v[196:197], v218 offset:32768
	ds_read_b64_tr_b16 v[198:199], v218 offset:33792
	ds_read_b64_tr_b16 v[202:203], v218 offset:34048
	ds_read_b64_tr_b16 v[200:201], v218 offset:33024
	s_waitcnt lgkmcnt(14)
	v_mfma_f32_32x32x16_bf16 v[48:63], v[32:35], v[64:67], 0
	v_add_f32_e32 v222, v96, v97
	v_add_f32_e32 v223, v109, v110
	v_add_f32_e32 v222, v98, v222
	v_add_f32_e32 v223, v111, v223
	s_andn2_b64 vcc, exec, s[10:11]
	v_mfma_f32_32x32x16_bf16 v[32:47], v[36:39], v[64:67], 0
	v_add_f32_e32 v222, v99, v222
	v_add_f32_e32 v223, v114, v223
	v_add_f32_e32 v222, v104, v222
	v_add_f32_e32 v223, v115, v223
	v_mfma_f32_32x32x16_bf16 v[48:63], v[140:143], v[68:71], v[48:63]
	v_add_f32_e32 v222, v105, v222
	v_add_f32_e32 v223, v116, v223
	v_add_f32_e32 v222, v106, v222
	v_add_f32_e32 v223, v117, v223
	v_mfma_f32_32x32x16_bf16 v[32:47], v[146:149], v[68:71], v[32:47]
	v_add_f32_e32 v222, v107, v222
	v_add_f32_e32 v223, v118, v223
	v_add_f32_e32 v222, v119, v222
	v_add_f32_e32 v223, v138, v223
	v_mfma_f32_32x32x16_bf16 v[48:63], v[152:155], v[72:75], v[48:63]
	v_add_f32_e32 v222, v120, v222
	v_add_f32_e32 v223, v137, v223
	v_add_f32_e32 v222, v126, v222
	v_add_f32_e32 v223, v136, v223
	v_mfma_f32_32x32x16_bf16 v[32:47], v[160:163], v[72:75], v[32:47]
	v_add_f32_e32 v222, v125, v222
	v_add_f32_e32 v223, v134, v223
	v_add_f32_e32 v222, v124, v222
	v_add_f32_e32 v223, v131, v223
	v_mfma_f32_32x32x16_bf16 v[48:63], v[156:159], v[76:79], v[48:63]
	v_add_f32_e32 v222, v123, v222
	v_add_f32_e32 v223, v135, v223
	v_add_f32_e32 v222, v122, v222
	v_add_f32_e32 v223, v133, v223
	v_mfma_f32_32x32x16_bf16 v[32:47], v[164:167], v[76:79], v[32:47]
	v_add_f32_e32 v222, v121, v222
	v_add_f32_e32 v223, v127, v223
	v_add_f32_e32 v222, v222, v223
	s_nop 10
	v_exp_f32_e32 v48, v48
	v_exp_f32_e32 v141, v58
	v_exp_f32_e32 v140, v59
	v_exp_f32_e32 v60, v60
	v_exp_f32_e32 v59, v61
	v_exp_f32_e32 v58, v62
	v_exp_f32_e32 v139, v32
	v_exp_f32_e32 v32, v49
	v_exp_f32_e32 v49, v33
	v_exp_f32_e32 v33, v50
	v_exp_f32_e32 v50, v34
	v_exp_f32_e32 v34, v51
	v_exp_f32_e32 v51, v35
	v_exp_f32_e32 v35, v52
	v_exp_f32_e32 v52, v36
	v_exp_f32_e32 v36, v53
	v_exp_f32_e32 v53, v37
	v_exp_f32_e32 v37, v54
	v_exp_f32_e32 v54, v38
	v_exp_f32_e32 v38, v55
	v_cvt_pk_bf16_f32 v146, v48, v32
	v_cvt_pk_bf16_f32 v147, v33, v34
	v_cvt_pk_bf16_f32 v148, v35, v36
	v_cvt_pk_bf16_f32 v149, v37, v38
	v_exp_f32_e32 v39, v39
	v_mfma_f32_32x32x16_bf16 v[0:15], v[168:171], v[146:149], v[0:15]
	v_exp_f32_e32 v55, v56
	v_exp_f32_e32 v56, v57
	v_exp_f32_e32 v57, v63
	v_cvt_pk_bf16_f32 v152, v139, v49
	v_cvt_pk_bf16_f32 v153, v50, v51
	v_cvt_pk_bf16_f32 v154, v52, v53
	v_cvt_pk_bf16_f32 v155, v54, v39
	s_waitcnt lgkmcnt(12)
	v_mfma_f32_32x32x16_bf16 v[16:31], v[172:175], v[146:149], v[16:31]
	v_cvt_pk_bf16_f32 v146, v55, v56
	v_cvt_pk_bf16_f32 v147, v141, v140
	v_cvt_pk_bf16_f32 v148, v60, v59
	v_cvt_pk_bf16_f32 v149, v58, v57
	v_exp_f32_e32 v63, v40
	v_exp_f32_e32 v62, v41
	v_exp_f32_e32 v61, v42
	s_waitcnt lgkmcnt(10)
	v_mfma_f32_32x32x16_bf16 v[0:15], v[176:179], v[146:149], v[0:15]
	v_exp_f32_e32 v43, v43
	v_exp_f32_e32 v41, v44
	v_exp_f32_e32 v44, v45
	v_exp_f32_e32 v42, v46
	v_exp_f32_e32 v40, v47
	s_waitcnt lgkmcnt(8)
	v_mfma_f32_32x32x16_bf16 v[16:31], v[180:183], v[146:149], v[16:31]
	v_add_f32_e32 v224, v48, v32
	v_add_f32_e32 v225, v139, v49
	v_add_f32_e32 v224, v33, v224
	v_add_f32_e32 v225, v50, v225
	v_add_f32_e32 v224, v34, v224
	v_add_f32_e32 v225, v51, v225
	v_add_f32_e32 v224, v35, v224
	v_add_f32_e32 v225, v52, v225
	v_cvt_pk_bf16_f32 v146, v63, v62
	v_cvt_pk_bf16_f32 v147, v61, v43
	v_cvt_pk_bf16_f32 v148, v41, v44
	v_cvt_pk_bf16_f32 v149, v42, v40
	s_waitcnt lgkmcnt(6)
	v_mfma_f32_32x32x16_bf16 v[0:15], v[184:187], v[152:155], v[0:15]
	v_add_f32_e32 v224, v36, v224
	v_add_f32_e32 v225, v53, v225
	v_add_f32_e32 v224, v37, v224
	v_add_f32_e32 v225, v54, v225
	v_add_f32_e32 v224, v38, v224
	v_add_f32_e32 v225, v39, v225
	v_add_f32_e32 v224, v55, v224
	v_add_f32_e32 v225, v63, v225
	s_waitcnt lgkmcnt(4)
	v_mfma_f32_32x32x16_bf16 v[16:31], v[188:191], v[152:155], v[16:31]
	v_add_f32_e32 v224, v56, v224
	v_add_f32_e32 v225, v62, v225
	v_add_f32_e32 v224, v141, v224
	v_add_f32_e32 v225, v61, v225
	v_add_f32_e32 v224, v140, v224
	v_add_f32_e32 v225, v43, v225
	v_add_f32_e32 v224, v60, v224
	v_add_f32_e32 v225, v41, v225
	s_waitcnt lgkmcnt(2)
	v_mfma_f32_32x32x16_bf16 v[0:15], v[196:199], v[146:149], v[0:15]
	v_add_f32_e32 v224, v59, v224
	v_add_f32_e32 v225, v44, v225
	v_add_f32_e32 v224, v58, v224
	v_add_f32_e32 v225, v42, v225
	v_add_f32_e32 v224, v57, v224
	v_add_f32_e32 v225, v40, v225
	v_add_f32_e32 v224, v224, v225
	s_waitcnt lgkmcnt(0)
	v_mfma_f32_32x32x16_bf16 v[16:31], v[200:203], v[146:149], v[16:31]
	s_cbranch_vccnz .LBB0_586
	s_cmp_ge_u32 s14, s12
	s_cbranch_scc1 .Lgqa_w1_tail
	s_waitcnt vmcnt(3)
	ds_write_b128 v193, v[80:83]
	s_waitcnt vmcnt(2)
	ds_write_b128 v219, v[84:87] offset:9216
	s_branch .LBB0_586

.LBB0_586:
	v_add_f32_e32 v222, v222, v224
	v_add_f32_e32 v108, v108, v222
	v_lshl_add_u64 v[100:101], v[100:101], 0, s[84:85]
	s_andn2_b64 vcc, exec, s[8:9]
	v_lshl_add_u64 v[102:103], v[102:103], 0, s[84:85]
	s_waitcnt lgkmcnt(0)
	s_barrier
	s_cbranch_vccz .LBB0_552
	s_mov_b32 s14, s13
	s_branch .LBB0_578
